# prep loops: masked boundary-row loads no longer branch around their block on exec==0 (22 s_cbranch_execz removed; exec masking kept)
# speedup vs baseline: 1.0014x; 1.0014x over previous
.LBB0_317:
	v_ashrrev_i32_e32 v36, 5, v39
	s_mov_b32 s0, 0x8000
	v_cmp_gt_i32_e32 vcc, s0, v36
	v_and_b32_e32 v30, 0xf8, v74
	v_mov_b64_e32 v[2:3], s[70:71]
	v_cndmask_b32_e32 v0, v222, v223, vcc
	v_and_b32_e32 v1, v0, v36
	v_mad_i64_i32 v[2:3], s[2:3], v36, s77, v[2:3]
	v_lshlrev_b32_e32 v8, 1, v30
	v_mov_b32_e32 v10, 0
	v_cmp_ne_u32_e64 s[0:1], 0, v1
	v_lshl_add_u64 v[26:27], v[2:3], 0, v[8:9]
	v_mov_b32_e32 v4, 0
	v_mov_b32_e32 v5, 0
	v_mov_b32_e32 v6, 0
	v_mov_b32_e32 v7, 0
	s_and_saveexec_b64 s[4:5], s[0:1]
	v_add_co_u32_e32 v2, vcc, 0xfffff000, v26
	s_nop 1
	v_addc_co_u32_e32 v3, vcc, -1, v27, vcc
	global_load_dwordx4 v[4:7], v[2:3], off offset:-3072
.LBB0_319:
	s_or_b64 exec, exec, s[4:5]
	global_load_dwordx4 v[14:17], v[26:27], off
	v_cmp_ne_u32_e64 s[4:5], v1, v0
	v_mov_b32_e32 v11, 0
	v_mov_b32_e32 v12, 0
	v_mov_b32_e32 v13, 0
	s_and_saveexec_b64 s[18:19], s[4:5]
	v_add_co_u32_e32 v0, vcc, 0x1000, v26
	s_nop 1
	v_addc_co_u32_e32 v1, vcc, 0, v27, vcc
	global_load_dwordx4 v[10:13], v[0:1], off offset:3072
.LBB0_321:
	s_or_b64 exec, exec, s[18:19]
	v_mov_b32_e32 v0, 0
	v_mov_b32_e32 v18, 0
	v_mov_b32_e32 v19, 0
	v_mov_b32_e32 v20, 0
	v_mov_b32_e32 v21, 0
	s_and_saveexec_b64 s[18:19], s[0:1]
	v_add_co_u32_e32 v2, vcc, 0xfffff000, v26
	s_nop 1
	v_addc_co_u32_e32 v3, vcc, -1, v27, vcc
	global_load_dwordx4 v[18:21], v[2:3], off offset:-2048
.LBB0_323:
	s_or_b64 exec, exec, s[18:19]
	global_load_dwordx4 v[22:25], v[26:27], off offset:1024
	v_mov_b32_e32 v1, 0
	v_mov_b32_e32 v2, 0
	v_mov_b32_e32 v3, 0
	s_and_saveexec_b64 s[0:1], s[4:5]
	v_add_co_u32_e32 v0, vcc, 0x2000, v26
	s_nop 1
	v_addc_co_u32_e32 v1, vcc, 0, v27, vcc
	global_load_dwordx4 v[0:3], v[0:1], off
.LBB0_325:
	s_or_b64 exec, exec, s[0:1]
	global_load_dwordx4 v[100:103], v[26:27], off offset:512
	global_load_dwordx4 v[104:107], v[26:27], off offset:1536
	v_readlane_b32 s0, v254, 48
	s_waitcnt vmcnt(3)
	v_lshlrev_b32_e32 v28, 16, v18
	v_and_b32_e32 v29, 0xffff0000, v18
	s_waitcnt vmcnt(2)
	v_lshlrev_b32_e32 v32, 16, v22
	v_and_b32_e32 v33, 0xffff0000, v22
	v_lshlrev_b32_e32 v62, 16, v19
	v_and_b32_e32 v63, 0xffff0000, v19
	v_lshlrev_b32_e32 v50, 16, v20
	v_and_b32_e32 v51, 0xffff0000, v20
	v_lshlrev_b32_e32 v40, 16, v21
	v_and_b32_e32 v41, 0xffff0000, v21
	v_lshlrev_b32_e32 v18, 16, v4
	v_and_b32_e32 v19, 0xffff0000, v4
	v_lshlrev_b32_e32 v20, 16, v14
	v_and_b32_e32 v21, 0xffff0000, v14
	v_lshlrev_b32_e32 v38, 2, v30
	v_readlane_b32 s1, v254, 49
	v_lshlrev_b32_e32 v68, 16, v23
	v_and_b32_e32 v69, 0xffff0000, v23
	v_lshlrev_b32_e32 v54, 16, v24
	v_and_b32_e32 v55, 0xffff0000, v24
	v_lshlrev_b32_e32 v44, 16, v25
	v_and_b32_e32 v45, 0xffff0000, v25
	v_lshlrev_b32_e32 v72, 16, v10
	v_and_b32_e32 v73, 0xffff0000, v10
	v_lshlrev_b32_e32 v64, 16, v11
	v_and_b32_e32 v65, 0xffff0000, v11
	v_lshlrev_b32_e32 v52, 16, v12
	v_and_b32_e32 v53, 0xffff0000, v12
	v_lshlrev_b32_e32 v42, 16, v13
	v_and_b32_e32 v43, 0xffff0000, v13
	v_lshlrev_b32_e32 v66, 16, v5
	v_and_b32_e32 v67, 0xffff0000, v5
	v_lshlrev_b32_e32 v56, 16, v6
	v_and_b32_e32 v57, 0xffff0000, v6
	v_lshlrev_b32_e32 v46, 16, v7
	v_and_b32_e32 v47, 0xffff0000, v7
	v_lshlrev_b32_e32 v70, 16, v15
	v_and_b32_e32 v71, 0xffff0000, v15
	v_lshlrev_b32_e32 v60, 16, v16
	v_and_b32_e32 v61, 0xffff0000, v16
	v_lshlrev_b32_e32 v48, 16, v17
	v_and_b32_e32 v49, 0xffff0000, v17
	s_waitcnt vmcnt(0)
	v_mov_b64_e32 v[10:11], v[100:101]
	v_mov_b64_e32 v[12:13], v[102:103]
	v_mov_b64_e32 v[4:5], v[104:105]
	v_mov_b64_e32 v[6:7], v[106:107]
	v_pk_mul_f32 v[22:23], v[20:21], v[32:33]
	v_mov_b64_e32 v[14:15], v[88:89]
	v_mov_b64_e32 v[16:17], v[90:91]
	v_mov_b64_e32 v[24:25], v[84:85]
	v_mov_b64_e32 v[26:27], v[86:87]
	v_pk_mul_f32 v[32:33], v[18:19], v[28:29]
	v_mov_b64_e32 v[18:19], v[96:97]
	v_mov_b64_e32 v[20:21], v[98:99]
	v_mov_b64_e32 v[28:29], v[92:93]
	v_mov_b64_e32 v[30:31], v[94:95]
	v_lshlrev_b32_e32 v78, 16, v0
	v_and_b32_e32 v79, 0xffff0000, v0
	v_pk_mul_f32 v[72:73], v[72:73], v[78:79]
	v_pk_mul_f32 v[62:63], v[66:67], v[62:63]
	v_ashrrev_i32_e32 v37, 31, v36
	s_waitcnt vmcnt(5)
	v_lshlrev_b32_e32 v80, 16, v10
	s_waitcnt vmcnt(4)
	v_lshlrev_b32_e32 v0, 16, v4
	v_and_b32_e32 v81, 0xffff0000, v10
	v_and_b32_e32 v4, 0xffff0000, v4
	v_mul_f32_e32 v10, 0xbfb8aa3b, v0
	s_waitcnt vmcnt(0)
	v_pk_mul_f32 v[22:23], v[22:23], v[28:29]
	v_exp_f32_e32 v82, v10
	v_pk_fma_f32 v[28:29], v[32:33], v[24:25], v[22:23]
	v_mov_b64_e32 v[22:23], v[112:113]
	v_mov_b64_e32 v[24:25], v[114:115]
	v_mov_b64_e32 v[32:33], v[108:109]
	v_mov_b64_e32 v[34:35], v[110:111]
	v_mul_f32_e32 v10, 0xbfb8aa3b, v4
	v_exp_f32_e32 v83, v10
	s_waitcnt vmcnt(0)
	v_pk_fma_f32 v[28:29], v[72:73], v[32:33], v[28:29]
	v_pk_add_f32 v[32:33], v[82:83], 1.0 op_sel_hi:[1,0]
	v_pk_mul_f32 v[28:29], v[28:29], v[80:81]
	v_div_scale_f32 v10, s[0:1], v33, v33, v4
	v_rcp_f32_e32 v72, v10
	s_nop 0
	v_fma_f32 v73, -v10, v72, 1.0
	v_fmac_f32_e32 v72, v73, v72
	v_div_scale_f32 v73, vcc, v4, v33, v4
	v_mul_f32_e32 v75, v73, v72
	v_fma_f32 v77, -v10, v75, v73
	v_fmac_f32_e32 v75, v77, v72
	v_fma_f32 v10, -v10, v75, v73
	v_div_fmas_f32 v10, v10, v72, v75
	v_div_fixup_f32 v33, v10, v33, v4
	v_div_scale_f32 v4, s[0:1], v32, v32, v0
	v_rcp_f32_e32 v10, v4
	s_nop 0
	v_fma_f32 v72, -v4, v10, 1.0
	v_fmac_f32_e32 v10, v72, v10
	v_div_scale_f32 v72, vcc, v0, v32, v0
	v_mul_f32_e32 v73, v72, v10
	v_fma_f32 v75, -v4, v73, v72
	v_fmac_f32_e32 v73, v75, v10
	v_fma_f32 v4, -v4, v73, v72
	v_div_fmas_f32 v4, v4, v10, v73
	v_div_fixup_f32 v32, v4, v32, v0
	v_pk_mul_f32 v[28:29], v[28:29], v[32:33]
	v_pk_mul_f32 v[32:33], v[70:71], v[68:69]
	v_lshlrev_b32_e32 v68, 16, v5
	v_and_b32_e32 v69, 0xffff0000, v5
	v_mul_f32_e32 v4, 0xbfb8aa3b, v68
	v_mul_f32_e32 v5, 0xbfb8aa3b, v69
	v_exp_f32_e32 v4, v4
	v_exp_f32_e32 v5, v5
	v_lshlrev_b32_e32 v0, 16, v1
	v_and_b32_e32 v1, 0xffff0000, v1
	v_pk_mul_f32 v[30:31], v[32:33], v[30:31]
	v_pk_mul_f32 v[0:1], v[64:65], v[0:1]
	v_pk_fma_f32 v[26:27], v[62:63], v[26:27], v[30:31]
	v_lshlrev_b32_e32 v10, 16, v11
	v_and_b32_e32 v11, 0xffff0000, v11
	v_pk_fma_f32 v[0:1], v[0:1], v[34:35], v[26:27]
	v_pk_add_f32 v[4:5], v[4:5], 1.0 op_sel_hi:[1,0]
	v_pk_mul_f32 v[0:1], v[0:1], v[10:11]
	v_div_scale_f32 v10, s[0:1], v5, v5, v69
	v_rcp_f32_e32 v11, v10
	v_pk_mul_f32 v[32:33], v[56:57], v[50:51]
	v_add_u32_e32 v72, s34, v39
	v_fma_f32 v26, -v10, v11, 1.0
	v_fmac_f32_e32 v11, v26, v11
	v_div_scale_f32 v26, vcc, v69, v5, v69
	v_mul_f32_e32 v27, v26, v11
	v_fma_f32 v30, -v10, v27, v26
	v_fmac_f32_e32 v27, v30, v11
	v_fma_f32 v10, -v10, v27, v26
	v_div_fmas_f32 v10, v10, v11, v27
	v_div_fixup_f32 v5, v10, v5, v69
	v_div_scale_f32 v10, s[0:1], v4, v4, v68
	v_rcp_f32_e32 v11, v10
	s_nop 0
	v_fma_f32 v26, -v10, v11, 1.0
	v_fmac_f32_e32 v11, v26, v11
	v_div_scale_f32 v26, vcc, v68, v4, v68
	v_mul_f32_e32 v27, v26, v11
	v_fma_f32 v30, -v10, v27, v26
	v_fmac_f32_e32 v27, v30, v11
	v_fma_f32 v10, -v10, v27, v26
	v_div_fmas_f32 v10, v10, v11, v27
	v_div_fixup_f32 v4, v10, v4, v68
	v_pk_mul_f32 v[0:1], v[4:5], v[0:1]
	v_pk_mul_f32 v[4:5], v[60:61], v[54:55]
	v_lshlrev_b32_e32 v10, 16, v2
	v_and_b32_e32 v11, 0xffff0000, v2
	v_pk_mul_f32 v[4:5], v[4:5], v[18:19]
	v_lshlrev_b32_e32 v2, 16, v6
	v_and_b32_e32 v6, 0xffff0000, v6
	v_pk_fma_f32 v[4:5], v[32:33], v[14:15], v[4:5]
	v_pk_mul_f32 v[10:11], v[52:53], v[10:11]
	v_lshlrev_b32_e32 v26, 16, v12
	v_and_b32_e32 v27, 0xffff0000, v12
	v_mul_f32_e32 v12, 0xbfb8aa3b, v2
	v_pk_fma_f32 v[4:5], v[10:11], v[22:23], v[4:5]
	v_mul_f32_e32 v10, 0xbfb8aa3b, v6
	v_exp_f32_e32 v30, v12
	v_exp_f32_e32 v31, v10
	v_pk_mul_f32 v[4:5], v[4:5], v[26:27]
	v_pk_add_f32 v[10:11], v[30:31], 1.0 op_sel_hi:[1,0]
	s_nop 0
	v_div_scale_f32 v12, s[0:1], v11, v11, v6
	v_rcp_f32_e32 v14, v12
	s_nop 0
	v_fma_f32 v15, -v12, v14, 1.0
	v_fmac_f32_e32 v14, v15, v14
	v_div_scale_f32 v15, vcc, v6, v11, v6
	v_mul_f32_e32 v18, v15, v14
	v_fma_f32 v19, -v12, v18, v15
	v_fmac_f32_e32 v18, v19, v14
	v_fma_f32 v12, -v12, v18, v15
	v_div_fmas_f32 v12, v12, v14, v18
	v_div_fixup_f32 v11, v12, v11, v6
	v_div_scale_f32 v6, s[0:1], v10, v10, v2
	v_rcp_f32_e32 v12, v6
	v_and_b32_e32 v19, 0xffff0000, v7
	v_fma_f32 v14, -v6, v12, 1.0
	v_fmac_f32_e32 v12, v14, v12
	v_div_scale_f32 v14, vcc, v2, v10, v2
	v_mul_f32_e32 v15, v14, v12
	v_fma_f32 v18, -v6, v15, v14
	v_fmac_f32_e32 v15, v18, v12
	v_fma_f32 v6, -v6, v15, v14
	v_div_fmas_f32 v6, v6, v12, v15
	v_lshlrev_b32_e32 v18, 16, v7
	v_div_fixup_f32 v10, v6, v10, v2
	v_mul_f32_e32 v6, 0xbfb8aa3b, v18
	v_mul_f32_e32 v7, 0xbfb8aa3b, v19
	v_exp_f32_e32 v6, v6
	v_exp_f32_e32 v7, v7
	v_pk_mul_f32 v[4:5], v[10:11], v[4:5]
	v_pk_mul_f32 v[10:11], v[48:49], v[44:45]
	v_lshlrev_b32_e32 v2, 16, v3
	v_and_b32_e32 v3, 0xffff0000, v3
	v_pk_mul_f32 v[14:15], v[46:47], v[40:41]
	v_pk_mul_f32 v[10:11], v[10:11], v[20:21]
	v_pk_mul_f32 v[2:3], v[42:43], v[2:3]
	v_pk_fma_f32 v[10:11], v[14:15], v[16:17], v[10:11]
	v_pk_add_f32 v[6:7], v[6:7], 1.0 op_sel_hi:[1,0]
	v_pk_fma_f32 v[2:3], v[2:3], v[24:25], v[10:11]
	v_div_scale_f32 v10, s[0:1], v7, v7, v19
	v_rcp_f32_e32 v11, v10
	v_lshlrev_b32_e32 v12, 16, v13
	v_and_b32_e32 v13, 0xffff0000, v13
	v_pk_mul_f32 v[2:3], v[2:3], v[12:13]
	v_fma_f32 v12, -v10, v11, 1.0
	v_fmac_f32_e32 v11, v12, v11
	v_div_scale_f32 v12, vcc, v19, v7, v19
	v_mul_f32_e32 v13, v12, v11
	v_fma_f32 v14, -v10, v13, v12
	v_fmac_f32_e32 v13, v14, v11
	v_fma_f32 v10, -v10, v13, v12
	v_div_fmas_f32 v10, v10, v11, v13
	v_div_fixup_f32 v7, v10, v7, v19
	v_div_scale_f32 v10, s[0:1], v6, v6, v18
	v_rcp_f32_e32 v11, v10
	v_readlane_b32 s0, v251, 59
	v_readlane_b32 s1, v251, 60
	v_cvt_pk_bf16_f32 v4, v4, v5
	v_fma_f32 v12, -v10, v11, 1.0
	v_fmac_f32_e32 v11, v12, v11
	v_div_scale_f32 v12, vcc, v18, v6, v18
	v_mul_f32_e32 v13, v12, v11
	v_fma_f32 v14, -v10, v13, v12
	v_fmac_f32_e32 v13, v14, v11
	v_fma_f32 v10, -v10, v13, v12
	v_div_fmas_f32 v10, v10, v11, v13
	v_div_fixup_f32 v6, v10, v6, v18
	v_pk_mul_f32 v[6:7], v[6:7], v[2:3]
	v_cvt_pk_bf16_f32 v3, v0, v1
	v_lshlrev_b64 v[0:1], 11, v[36:37]
	v_lshl_add_u64 v[0:1], s[0:1], 0, v[0:1]
	s_mov_b32 s0, 0x110000
	v_cvt_pk_bf16_f32 v2, v28, v29
	v_cvt_pk_bf16_f32 v5, v6, v7
	v_lshl_add_u64 v[0:1], v[0:1], 0, v[8:9]
	v_cmp_gt_i32_e32 vcc, s0, v72
	s_mov_b64 s[0:1], -1
	global_store_dwordx4 v[0:1], v[2:5], off
	s_and_saveexec_b64 s[18:19], vcc
	s_cbranch_execz .LBB0_316
	v_ashrrev_i32_e32 v36, 5, v72
	s_mov_b32 s0, 0x8000
	v_cmp_gt_i32_e32 vcc, s0, v36
	v_mov_b64_e32 v[2:3], s[70:71]
	v_mad_i64_i32 v[2:3], s[2:3], v36, s77, v[2:3]
	v_cndmask_b32_e32 v0, v222, v223, vcc
	v_and_b32_e32 v1, v0, v36
	v_mov_b32_e32 v10, 0
	v_cmp_ne_u32_e64 s[0:1], 0, v1
	v_lshl_add_u64 v[26:27], v[2:3], 0, v[8:9]
	v_mov_b32_e32 v4, 0
	v_mov_b32_e32 v5, 0
	v_mov_b32_e32 v6, 0
	v_mov_b32_e32 v7, 0
	s_and_saveexec_b64 s[4:5], s[0:1]
	v_add_co_u32_e32 v2, vcc, 0xfffff000, v26
	s_nop 1
	v_addc_co_u32_e32 v3, vcc, -1, v27, vcc
	global_load_dwordx4 v[4:7], v[2:3], off offset:-3072
.LBB0_328:
	s_or_b64 exec, exec, s[4:5]
	global_load_dwordx4 v[14:17], v[26:27], off
	v_cmp_ne_u32_e64 s[4:5], v1, v0
	v_mov_b32_e32 v11, 0
	v_mov_b32_e32 v12, 0
	v_mov_b32_e32 v13, 0
	s_and_saveexec_b64 s[24:25], s[4:5]
	v_add_co_u32_e32 v0, vcc, 0x1000, v26
	s_nop 1
	v_addc_co_u32_e32 v1, vcc, 0, v27, vcc
	global_load_dwordx4 v[10:13], v[0:1], off offset:3072
.LBB0_330:
	s_or_b64 exec, exec, s[24:25]
	v_mov_b32_e32 v0, 0
	v_mov_b32_e32 v18, 0
	v_mov_b32_e32 v19, 0
	v_mov_b32_e32 v20, 0
	v_mov_b32_e32 v21, 0
	s_and_saveexec_b64 s[24:25], s[0:1]
	v_add_co_u32_e32 v2, vcc, 0xfffff000, v26
	s_nop 1
	v_addc_co_u32_e32 v3, vcc, -1, v27, vcc
	global_load_dwordx4 v[18:21], v[2:3], off offset:-2048

.LBB0_341:
	v_ashrrev_i32_e32 v33, 5, v32
	s_mov_b32 s2, 0x8000
	v_and_b32_e32 v8, 0xf8, v44
	v_cmp_gt_i32_e32 vcc, s2, v33
	v_mov_b64_e32 v[4:5], s[70:71]
	v_mad_i64_i32 v[4:5], s[2:3], v33, s77, v[4:5]
	v_cndmask_b32_e32 v1, v222, v223, vcc
	v_lshlrev_b32_e32 v36, 1, v8
	v_mov_b32_e32 v37, v9
	v_and_b32_e32 v2, v1, v33
	v_lshl_add_u64 v[4:5], v[4:5], 0, v[36:37]
	s_mov_b64 s[2:3], 0x1400
	v_mov_b32_e32 v0, 0
	v_cmp_ne_u32_e32 vcc, 0, v2
	v_lshl_add_u64 v[14:15], v[4:5], 0, s[2:3]
	v_mov_b32_e32 v4, 0
	v_mov_b32_e32 v5, 0
	v_mov_b32_e32 v6, 0
	v_mov_b32_e32 v7, 0
	s_and_saveexec_b64 s[4:5], vcc
	v_add_co_u32_e32 v4, vcc, 0xfffff000, v14
	s_nop 1
	v_addc_co_u32_e32 v5, vcc, -1, v15, vcc
	global_load_dwordx4 v[4:7], v[4:5], off offset:-3072
.LBB0_343:
	s_or_b64 exec, exec, s[4:5]
	global_load_dwordx4 v[10:13], v[14:15], off
	v_cmp_ne_u32_e32 vcc, v2, v1
	v_mov_b32_e32 v1, 0
	v_mov_b32_e32 v2, 0
	v_mov_b32_e32 v3, 0
	s_and_saveexec_b64 s[4:5], vcc
	v_add_co_u32_e32 v0, vcc, 0x1000, v14
	s_nop 1
	v_addc_co_u32_e32 v1, vcc, 0, v15, vcc
	global_load_dwordx4 v[0:3], v[0:1], off offset:3072
.LBB0_345:
	s_or_b64 exec, exec, s[4:5]
	v_readlane_b32 s4, v254, 50
	v_lshlrev_b32_e32 v8, 2, v8
	v_readlane_b32 s5, v254, 51
	s_nop 4
	global_load_dwordx4 v[14:17], v8, s[4:5] offset:16
	global_load_dwordx4 v[28:31], v8, s[4:5]
	global_load_dwordx4 v[18:21], v8, s[4:5] offset:3088
	global_load_dwordx4 v[46:49], v8, s[4:5] offset:3072
	v_lshl_add_u64 v[40:41], s[4:5], 0, v[8:9]
	s_mov_b64 s[2:3], 0x1800
	s_waitcnt vmcnt(4)
	v_lshlrev_b32_e32 v22, 16, v10
	v_and_b32_e32 v23, 0xffff0000, v10
	v_lshl_add_u64 v[38:39], v[40:41], 0, s[2:3]
	v_lshlrev_b32_e32 v24, 16, v4
	v_and_b32_e32 v25, 0xffff0000, v4
	s_movk_i32 s2, 0x1000
	v_lshlrev_b32_e32 v26, 16, v0
	v_and_b32_e32 v27, 0xffff0000, v0
	s_mov_b64 s[6:7], -1
	s_waitcnt vmcnt(0)
	v_pk_mul_f32 v[22:23], v[46:47], v[22:23]
	s_nop 0
	v_pk_fma_f32 v[28:29], v[28:29], v[24:25], v[22:23]
	v_add_co_u32_e32 v22, vcc, s2, v40
	v_readlane_b32 s2, v254, 52
	s_nop 0
	v_addc_co_u32_e32 v23, vcc, 0, v41, vcc
	global_load_dwordx4 v[50:53], v[22:23], off offset:2048
	s_nop 0
	global_load_dwordx4 v[22:25], v[38:39], off offset:16
	v_readlane_b32 s3, v254, 53
	s_waitcnt vmcnt(1)
	v_pk_fma_f32 v[34:35], v[50:51], v[26:27], v[28:29]
	s_nop 2
	global_load_dwordx4 v[26:29], v8, s[2:3] offset:16
	global_load_dwordx4 v[54:57], v8, s[2:3]
	s_waitcnt vmcnt(0)
	v_pk_add_f32 v[34:35], v[54:55], v[34:35]
	s_nop 0
	v_mul_f32_e32 v0, 0xbfb8aa3b, v34
	v_exp_f32_e32 v42, v0
	v_mul_f32_e32 v0, 0xbfb8aa3b, v35
	v_exp_f32_e32 v43, v0
	s_nop 0
	v_pk_add_f32 v[42:43], v[42:43], 1.0 op_sel_hi:[1,0]
	s_nop 0
	v_div_scale_f32 v0, s[2:3], v43, v43, v35
	v_rcp_f32_e32 v4, v0
	s_nop 0
	v_fma_f32 v10, -v0, v4, 1.0
	v_fmac_f32_e32 v4, v10, v4
	v_div_scale_f32 v10, vcc, v35, v43, v35
	v_mul_f32_e32 v37, v10, v4
	v_fma_f32 v45, -v0, v37, v10
	v_fmac_f32_e32 v37, v45, v4
	v_fma_f32 v0, -v0, v37, v10
	v_div_fmas_f32 v0, v0, v4, v37
	v_div_scale_f32 v4, s[2:3], v42, v42, v34
	v_rcp_f32_e32 v10, v4
	v_div_fixup_f32 v0, v0, v43, v35
	v_add_u32_e32 v45, s34, v32
	v_fma_f32 v35, -v4, v10, 1.0
	v_fmac_f32_e32 v10, v35, v10
	v_div_scale_f32 v35, vcc, v34, v42, v34
	v_mul_f32_e32 v37, v35, v10
	v_fma_f32 v43, -v4, v37, v35
	v_fmac_f32_e32 v37, v43, v10
	v_fma_f32 v4, -v4, v37, v35
	v_div_fmas_f32 v4, v4, v10, v37
	v_lshlrev_b32_e32 v10, 16, v11
	v_and_b32_e32 v11, 0xffff0000, v11
	v_div_fixup_f32 v4, v4, v42, v34
	v_lshlrev_b32_e32 v34, 16, v5
	v_and_b32_e32 v35, 0xffff0000, v5
	v_pk_mul_f32 v[10:11], v[48:49], v[10:11]
	v_lshlrev_b32_e32 v42, 16, v1
	v_and_b32_e32 v43, 0xffff0000, v1
	v_pk_fma_f32 v[10:11], v[30:31], v[34:35], v[10:11]
	v_cvt_pk_bf16_f32 v0, v4, v0
	v_pk_fma_f32 v[10:11], v[52:53], v[42:43], v[10:11]
	s_nop 0
	v_pk_add_f32 v[10:11], v[56:57], v[10:11]
	s_nop 0
	v_mul_f32_e32 v1, 0xbfb8aa3b, v10
	v_exp_f32_e32 v30, v1
	v_mul_f32_e32 v1, 0xbfb8aa3b, v11
	v_exp_f32_e32 v31, v1
	s_nop 0
	v_pk_add_f32 v[30:31], v[30:31], 1.0 op_sel_hi:[1,0]
	s_nop 0
	v_div_scale_f32 v1, s[2:3], v31, v31, v11
	v_rcp_f32_e32 v5, v1
	s_nop 0
	v_fma_f32 v34, -v1, v5, 1.0
	v_fmac_f32_e32 v5, v34, v5
	v_div_scale_f32 v34, vcc, v11, v31, v11
	v_mul_f32_e32 v35, v34, v5
	v_fma_f32 v37, -v1, v35, v34
	v_fmac_f32_e32 v35, v37, v5
	v_fma_f32 v1, -v1, v35, v34
	v_div_fmas_f32 v1, v1, v5, v35
	v_div_scale_f32 v5, s[2:3], v30, v30, v10
	v_div_fixup_f32 v1, v1, v31, v11
	v_rcp_f32_e32 v11, v5
	v_mov_b32_e32 v37, v9
	v_fma_f32 v31, -v5, v11, 1.0
	v_fmac_f32_e32 v11, v31, v11
	v_div_scale_f32 v31, vcc, v10, v30, v10
	v_mul_f32_e32 v34, v31, v11
	v_fma_f32 v35, -v5, v34, v31
	v_fmac_f32_e32 v34, v35, v11
	v_fma_f32 v5, -v5, v34, v31
	v_div_fmas_f32 v5, v5, v11, v34
	v_div_fixup_f32 v5, v5, v30, v10
	v_lshlrev_b32_e32 v10, 16, v12
	v_and_b32_e32 v11, 0xffff0000, v12
	v_lshlrev_b32_e32 v30, 16, v6
	v_and_b32_e32 v31, 0xffff0000, v6
	v_pk_mul_f32 v[10:11], v[18:19], v[10:11]
	v_lshlrev_b32_e32 v34, 16, v2
	v_and_b32_e32 v35, 0xffff0000, v2
	v_pk_fma_f32 v[10:11], v[14:15], v[30:31], v[10:11]
	v_cvt_pk_bf16_f32 v1, v5, v1
	v_pk_fma_f32 v[10:11], v[22:23], v[34:35], v[10:11]
	s_nop 0
	v_pk_add_f32 v[10:11], v[26:27], v[10:11]
	s_nop 0
	v_mul_f32_e32 v2, 0xbfb8aa3b, v10
	v_exp_f32_e32 v14, v2
	v_mul_f32_e32 v2, 0xbfb8aa3b, v11
	v_exp_f32_e32 v15, v2
	s_nop 0
	v_pk_add_f32 v[14:15], v[14:15], 1.0 op_sel_hi:[1,0]
	s_nop 0
	v_div_scale_f32 v2, s[2:3], v15, v15, v11
	v_rcp_f32_e32 v6, v2
	s_nop 0
	v_fma_f32 v12, -v2, v6, 1.0
	v_fmac_f32_e32 v6, v12, v6
	v_div_scale_f32 v12, vcc, v11, v15, v11
	v_mul_f32_e32 v18, v12, v6
	v_fma_f32 v19, -v2, v18, v12
	v_fmac_f32_e32 v18, v19, v6
	v_fma_f32 v2, -v2, v18, v12
	v_div_fmas_f32 v2, v2, v6, v18
	v_div_fixup_f32 v12, v2, v15, v11
	v_div_scale_f32 v2, s[2:3], v14, v14, v10
	v_rcp_f32_e32 v6, v2
	s_nop 0
	v_fma_f32 v11, -v2, v6, 1.0
	v_fmac_f32_e32 v6, v11, v6
	v_div_scale_f32 v11, vcc, v10, v14, v10
	v_mul_f32_e32 v15, v11, v6
	v_fma_f32 v18, -v2, v15, v11
	v_fmac_f32_e32 v15, v18, v6
	v_fma_f32 v2, -v2, v15, v11
	v_div_fmas_f32 v2, v2, v6, v15
	v_div_fixup_f32 v14, v2, v14, v10
	v_lshlrev_b32_e32 v10, 16, v13
	v_and_b32_e32 v11, 0xffff0000, v13
	v_lshlrev_b32_e32 v6, 16, v7
	v_and_b32_e32 v7, 0xffff0000, v7
	v_pk_mul_f32 v[10:11], v[20:21], v[10:11]
	v_lshlrev_b32_e32 v2, 16, v3
	v_and_b32_e32 v3, 0xffff0000, v3
	v_pk_fma_f32 v[6:7], v[16:17], v[6:7], v[10:11]
	s_nop 0
	v_pk_fma_f32 v[2:3], v[24:25], v[2:3], v[6:7]
	s_nop 0
	v_pk_add_f32 v[2:3], v[28:29], v[2:3]
	s_nop 0
	v_mul_f32_e32 v6, 0xbfb8aa3b, v2
	v_mul_f32_e32 v7, 0xbfb8aa3b, v3
	v_exp_f32_e32 v6, v6
	v_exp_f32_e32 v7, v7
	s_nop 0
	v_pk_add_f32 v[6:7], v[6:7], 1.0 op_sel_hi:[1,0]
	s_nop 0
	v_div_scale_f32 v10, s[2:3], v7, v7, v3
	v_rcp_f32_e32 v11, v10
	s_nop 0
	v_fma_f32 v13, -v10, v11, 1.0
	v_fmac_f32_e32 v11, v13, v11
	v_div_scale_f32 v13, vcc, v3, v7, v3
	v_mul_f32_e32 v15, v13, v11
	v_fma_f32 v16, -v10, v15, v13
	v_fmac_f32_e32 v15, v16, v11
	v_fma_f32 v10, -v10, v15, v13
	v_div_fmas_f32 v10, v10, v11, v15
	v_div_fixup_f32 v3, v10, v7, v3
	v_div_scale_f32 v7, s[2:3], v6, v6, v2
	v_rcp_f32_e32 v10, v7
	v_readlane_b32 s2, v251, 43
	v_readlane_b32 s3, v251, 44
	v_fma_f32 v11, -v7, v10, 1.0
	v_fmac_f32_e32 v10, v11, v10
	v_div_scale_f32 v11, vcc, v2, v6, v2
	v_mul_f32_e32 v13, v11, v10
	v_fma_f32 v15, -v7, v13, v11
	v_fmac_f32_e32 v13, v15, v10
	v_fma_f32 v7, -v7, v13, v11
	v_mov_b64_e32 v[4:5], s[2:3]
	s_movk_i32 s2, 0x600
	v_div_fmas_f32 v7, v7, v10, v13
	v_mad_i64_i32 v[4:5], s[2:3], v33, s2, v[4:5]
	v_div_fixup_f32 v6, v7, v6, v2
	s_mov_b32 s2, 0x110000
	v_cvt_pk_bf16_f32 v2, v14, v12
	v_cvt_pk_bf16_f32 v3, v6, v3
	v_lshl_add_u64 v[4:5], v[4:5], 0, v[36:37]
	v_cmp_gt_i32_e32 vcc, s2, v45
	global_store_dwordx4 v[4:5], v[0:3], off
	s_and_saveexec_b64 s[4:5], vcc
	s_cbranch_execz .LBB0_340
	v_ashrrev_i32_e32 v46, 5, v45
	s_mov_b32 s2, 0x8000
	v_cmp_gt_i32_e32 vcc, s2, v46
	v_mov_b64_e32 v[4:5], s[70:71]
	v_mad_i64_i32 v[4:5], s[2:3], v46, s77, v[4:5]
	v_cndmask_b32_e32 v1, v222, v223, vcc
	v_and_b32_e32 v2, v1, v46
	v_lshl_add_u64 v[4:5], v[4:5], 0, v[36:37]
	s_mov_b64 s[2:3], 0x1400
	v_mov_b32_e32 v0, 0
	v_cmp_ne_u32_e32 vcc, 0, v2
	v_lshl_add_u64 v[14:15], v[4:5], 0, s[2:3]
	v_mov_b32_e32 v4, 0
	v_mov_b32_e32 v5, 0
	v_mov_b32_e32 v6, 0
	v_mov_b32_e32 v7, 0
	s_and_saveexec_b64 s[6:7], vcc
	v_add_co_u32_e32 v4, vcc, 0xfffff000, v14
	s_nop 1
	v_addc_co_u32_e32 v5, vcc, -1, v15, vcc
	global_load_dwordx4 v[4:7], v[4:5], off offset:-3072
.LBB0_348:
	s_or_b64 exec, exec, s[6:7]
	global_load_dwordx4 v[10:13], v[14:15], off
	v_cmp_ne_u32_e32 vcc, v2, v1
	v_mov_b32_e32 v1, 0
	v_mov_b32_e32 v2, 0
	v_mov_b32_e32 v3, 0
	s_and_saveexec_b64 s[6:7], vcc
	v_add_co_u32_e32 v0, vcc, 0x1000, v14
	s_nop 1
	v_addc_co_u32_e32 v1, vcc, 0, v15, vcc
	global_load_dwordx4 v[0:3], v[0:1], off offset:3072
.LBB0_350:
	s_or_b64 exec, exec, s[6:7]
	global_load_dwordx4 v[14:17], v[40:41], off offset:16
	global_load_dwordx4 v[28:31], v[40:41], off
	global_load_dwordx4 v[18:21], v[40:41], off offset:3088
	global_load_dwordx4 v[32:35], v[40:41], off offset:3072
	s_waitcnt vmcnt(4)
	v_lshlrev_b32_e32 v22, 16, v10
	v_and_b32_e32 v23, 0xffff0000, v10
	v_lshlrev_b32_e32 v24, 16, v4
	v_and_b32_e32 v25, 0xffff0000, v4
	v_readlane_b32 s2, v254, 52
	v_readlane_b32 s3, v254, 53
	v_lshlrev_b32_e32 v26, 16, v0
	v_and_b32_e32 v27, 0xffff0000, v0
	v_lshl_add_u64 v[42:43], s[2:3], 0, v[8:9]
	s_mov_b64 s[18:19], -1
	s_waitcnt vmcnt(0)
	v_pk_mul_f32 v[22:23], v[32:33], v[22:23]
	s_nop 0
	v_pk_fma_f32 v[28:29], v[28:29], v[24:25], v[22:23]
	global_load_dwordx4 v[22:25], v[38:39], off offset:16
	global_load_dwordx4 v[48:51], v[38:39], off
	s_waitcnt vmcnt(0)
	v_pk_fma_f32 v[32:33], v[48:49], v[26:27], v[28:29]
	global_load_dwordx4 v[26:29], v[42:43], off offset:16
	global_load_dwordx4 v[52:55], v[42:43], off
	s_waitcnt vmcnt(0)
	v_pk_add_f32 v[32:33], v[52:53], v[32:33]
	s_nop 0
	v_mul_f32_e32 v0, 0xbfb8aa3b, v32
	v_exp_f32_e32 v48, v0
	v_mul_f32_e32 v0, 0xbfb8aa3b, v33
	v_exp_f32_e32 v49, v0
	s_nop 0
	v_pk_add_f32 v[48:49], v[48:49], 1.0 op_sel_hi:[1,0]
	s_nop 0
	v_div_scale_f32 v0, s[2:3], v49, v49, v33
	v_rcp_f32_e32 v4, v0
	s_nop 0
	v_fma_f32 v8, -v0, v4, 1.0
	v_fmac_f32_e32 v4, v8, v4
	v_div_scale_f32 v8, vcc, v33, v49, v33
	v_mul_f32_e32 v10, v8, v4
	v_fma_f32 v37, -v0, v10, v8
	v_fmac_f32_e32 v10, v37, v4
	v_fma_f32 v0, -v0, v10, v8
	v_div_fmas_f32 v0, v0, v4, v10
	v_div_fixup_f32 v4, v0, v49, v33
	v_div_scale_f32 v0, s[2:3], v48, v48, v32
	v_rcp_f32_e32 v8, v0
	s_nop 0
	v_fma_f32 v10, -v0, v8, 1.0
	v_fmac_f32_e32 v8, v10, v8
	v_div_scale_f32 v10, vcc, v32, v48, v32
	v_mul_f32_e32 v33, v10, v8
	v_fma_f32 v37, -v0, v33, v10
	v_fmac_f32_e32 v33, v37, v8
	v_fma_f32 v0, -v0, v33, v10
	v_div_fmas_f32 v0, v0, v8, v33
	v_lshlrev_b32_e32 v10, 16, v11
	v_and_b32_e32 v11, 0xffff0000, v11
	v_div_fixup_f32 v8, v0, v48, v32
	v_lshlrev_b32_e32 v32, 16, v5
	v_and_b32_e32 v33, 0xffff0000, v5
	v_pk_mul_f32 v[10:11], v[34:35], v[10:11]
	v_lshlrev_b32_e32 v0, 16, v1
	v_and_b32_e32 v1, 0xffff0000, v1
	v_pk_fma_f32 v[10:11], v[30:31], v[32:33], v[10:11]
	v_mov_b32_e32 v37, v9
	v_pk_fma_f32 v[0:1], v[50:51], v[0:1], v[10:11]
	s_nop 0
	v_pk_add_f32 v[0:1], v[54:55], v[0:1]
	s_nop 0
	v_mul_f32_e32 v5, 0xbfb8aa3b, v0
	v_exp_f32_e32 v10, v5
	v_mul_f32_e32 v5, 0xbfb8aa3b, v1
	v_exp_f32_e32 v11, v5
	s_nop 0
	v_pk_add_f32 v[10:11], v[10:11], 1.0 op_sel_hi:[1,0]
	s_nop 0
	v_div_scale_f32 v5, s[2:3], v11, v11, v1
	v_rcp_f32_e32 v30, v5
	s_nop 0
	v_fma_f32 v31, -v5, v30, 1.0
	v_fmac_f32_e32 v30, v31, v30
	v_div_scale_f32 v31, vcc, v1, v11, v1
	v_mul_f32_e32 v32, v31, v30
	v_fma_f32 v33, -v5, v32, v31
	v_fmac_f32_e32 v32, v33, v30
	v_fma_f32 v5, -v5, v32, v31
	v_div_fmas_f32 v5, v5, v30, v32
	v_div_fixup_f32 v5, v5, v11, v1
	v_div_scale_f32 v1, s[2:3], v10, v10, v0
	v_rcp_f32_e32 v11, v1
	v_and_b32_e32 v33, 0xffff0000, v2
	v_fma_f32 v30, -v1, v11, 1.0
	v_fmac_f32_e32 v11, v30, v11
	v_div_scale_f32 v30, vcc, v0, v10, v0
	v_mul_f32_e32 v31, v30, v11
	v_fma_f32 v32, -v1, v31, v30
	v_fmac_f32_e32 v31, v32, v11
	v_fma_f32 v1, -v1, v31, v30
	v_div_fmas_f32 v1, v1, v11, v31
	v_div_fixup_f32 v10, v1, v10, v0
	v_lshlrev_b32_e32 v0, 16, v12
	v_and_b32_e32 v1, 0xffff0000, v12
	v_lshlrev_b32_e32 v30, 16, v6
	v_and_b32_e32 v31, 0xffff0000, v6
	v_pk_mul_f32 v[0:1], v[18:19], v[0:1]
	v_lshlrev_b32_e32 v32, 16, v2
	v_pk_fma_f32 v[0:1], v[14:15], v[30:31], v[0:1]
	s_nop 0
	v_pk_fma_f32 v[0:1], v[22:23], v[32:33], v[0:1]
	s_nop 0
	v_pk_add_f32 v[0:1], v[26:27], v[0:1]
	s_nop 0
	v_mul_f32_e32 v2, 0xbfb8aa3b, v0
	v_exp_f32_e32 v14, v2
	v_mul_f32_e32 v2, 0xbfb8aa3b, v1
	v_exp_f32_e32 v15, v2
	s_nop 0
	v_pk_add_f32 v[14:15], v[14:15], 1.0 op_sel_hi:[1,0]
	s_nop 0
	v_div_scale_f32 v2, s[2:3], v15, v15, v1
	v_rcp_f32_e32 v6, v2
	s_nop 0
	v_fma_f32 v11, -v2, v6, 1.0
	v_fmac_f32_e32 v6, v11, v6
	v_div_scale_f32 v11, vcc, v1, v15, v1
	v_mul_f32_e32 v12, v11, v6
	v_fma_f32 v18, -v2, v12, v11
	v_fmac_f32_e32 v12, v18, v6
	v_fma_f32 v2, -v2, v12, v11
	v_div_fmas_f32 v2, v2, v6, v12
	v_div_fixup_f32 v11, v2, v15, v1
	v_div_scale_f32 v1, s[2:3], v14, v14, v0
	v_rcp_f32_e32 v2, v1
	s_nop 0
	v_fma_f32 v6, -v1, v2, 1.0
	v_fmac_f32_e32 v2, v6, v2
	v_div_scale_f32 v6, vcc, v0, v14, v0
	v_mul_f32_e32 v12, v6, v2
	v_fma_f32 v15, -v1, v12, v6
	v_fmac_f32_e32 v12, v15, v2
	v_fma_f32 v1, -v1, v12, v6
	v_div_fmas_f32 v1, v1, v2, v12
	v_div_fixup_f32 v12, v1, v14, v0
	v_lshlrev_b32_e32 v0, 16, v13
	v_and_b32_e32 v1, 0xffff0000, v13
	v_lshlrev_b32_e32 v6, 16, v7
	v_and_b32_e32 v7, 0xffff0000, v7
	v_pk_mul_f32 v[0:1], v[20:21], v[0:1]
	v_lshlrev_b32_e32 v2, 16, v3
	v_and_b32_e32 v3, 0xffff0000, v3
	v_pk_fma_f32 v[0:1], v[16:17], v[6:7], v[0:1]
	s_nop 0
	v_pk_fma_f32 v[0:1], v[24:25], v[2:3], v[0:1]
	s_nop 0
	v_pk_add_f32 v[0:1], v[28:29], v[0:1]
	s_nop 0
	v_mul_f32_e32 v2, 0xbfb8aa3b, v0
	v_mul_f32_e32 v3, 0xbfb8aa3b, v1
	v_exp_f32_e32 v2, v2
	v_exp_f32_e32 v3, v3
	s_nop 0
	v_pk_add_f32 v[2:3], v[2:3], 1.0 op_sel_hi:[1,0]
	s_nop 0
	v_div_scale_f32 v6, s[2:3], v3, v3, v1
	v_rcp_f32_e32 v7, v6
	s_nop 0
	v_fma_f32 v13, -v6, v7, 1.0
	v_fmac_f32_e32 v7, v13, v7
	v_div_scale_f32 v13, vcc, v1, v3, v1
	v_mul_f32_e32 v14, v13, v7
	v_fma_f32 v15, -v6, v14, v13
	v_fmac_f32_e32 v14, v15, v7
	v_fma_f32 v6, -v6, v14, v13
	v_div_fmas_f32 v6, v6, v7, v14
	v_div_fixup_f32 v3, v6, v3, v1
	v_div_scale_f32 v1, s[2:3], v2, v2, v0
	v_rcp_f32_e32 v6, v1
	v_readlane_b32 s2, v251, 43
	v_readlane_b32 s3, v251, 44
	v_fma_f32 v7, -v1, v6, 1.0
	v_fmac_f32_e32 v6, v7, v6
	v_div_scale_f32 v7, vcc, v0, v2, v0
	v_mul_f32_e32 v13, v7, v6
	v_fma_f32 v14, -v1, v13, v7
	v_fmac_f32_e32 v13, v14, v6
	v_fma_f32 v1, -v1, v13, v7
	v_div_fmas_f32 v1, v1, v6, v13
	v_div_fixup_f32 v6, v1, v2, v0
	v_cvt_pk_bf16_f32 v0, v8, v4
	v_cvt_pk_bf16_f32 v1, v10, v5
	v_mov_b64_e32 v[4:5], s[2:3]
	s_movk_i32 s2, 0x600
	v_mad_i64_i32 v[4:5], s[2:3], v46, s2, v[4:5]
	v_add_u32_e32 v8, s34, v45
	s_mov_b32 s2, 0x110000
	v_cvt_pk_bf16_f32 v2, v12, v11
	v_cvt_pk_bf16_f32 v3, v6, v3
	v_lshl_add_u64 v[4:5], v[4:5], 0, v[36:37]
	v_cmp_gt_i32_e32 vcc, s2, v8
	global_store_dwordx4 v[4:5], v[0:3], off
	s_and_saveexec_b64 s[6:7], vcc
	s_cbranch_execz .LBB0_339
	v_ashrrev_i32_e32 v32, 5, v8
	s_mov_b32 s2, 0x8000
	v_cmp_gt_i32_e32 vcc, s2, v32
	v_mov_b64_e32 v[4:5], s[70:71]
	v_mad_i64_i32 v[4:5], s[2:3], v32, s77, v[4:5]
	v_cndmask_b32_e32 v1, v222, v223, vcc
	v_and_b32_e32 v2, v1, v32
	v_lshl_add_u64 v[4:5], v[4:5], 0, v[36:37]
	s_mov_b64 s[2:3], 0x1400
	v_mov_b32_e32 v0, 0
	v_cmp_ne_u32_e32 vcc, 0, v2
	v_lshl_add_u64 v[14:15], v[4:5], 0, s[2:3]
	v_mov_b32_e32 v4, 0
	v_mov_b32_e32 v5, 0
	v_mov_b32_e32 v6, 0
	v_mov_b32_e32 v7, 0
	s_and_saveexec_b64 s[18:19], vcc
	v_add_co_u32_e32 v4, vcc, 0xfffff000, v14
	s_nop 1
	v_addc_co_u32_e32 v5, vcc, -1, v15, vcc
	global_load_dwordx4 v[4:7], v[4:5], off offset:-3072
.LBB0_353:
	s_or_b64 exec, exec, s[18:19]
	global_load_dwordx4 v[10:13], v[14:15], off
	v_cmp_ne_u32_e32 vcc, v2, v1
	v_mov_b32_e32 v1, 0
	v_mov_b32_e32 v2, 0
	v_mov_b32_e32 v3, 0
	s_and_saveexec_b64 s[18:19], vcc
	v_add_co_u32_e32 v0, vcc, 0x1000, v14
	s_nop 1
	v_addc_co_u32_e32 v1, vcc, 0, v15, vcc
	global_load_dwordx4 v[0:3], v[0:1], off offset:3072
.LBB0_355:
	s_or_b64 exec, exec, s[18:19]
	global_load_dwordx4 v[14:17], v[40:41], off offset:16
	global_load_dwordx4 v[28:31], v[40:41], off
	global_load_dwordx4 v[18:21], v[40:41], off offset:3088
	global_load_dwordx4 v[46:49], v[40:41], off offset:3072
	s_waitcnt vmcnt(4)
	v_lshlrev_b32_e32 v22, 16, v10
	v_and_b32_e32 v23, 0xffff0000, v10
	v_lshlrev_b32_e32 v24, 16, v4
	v_and_b32_e32 v25, 0xffff0000, v4
	v_lshlrev_b32_e32 v26, 16, v0
	v_and_b32_e32 v27, 0xffff0000, v0
	v_add_u32_e32 v8, s34, v8
	s_mov_b64 s[24:25], -1
	s_waitcnt vmcnt(0)
	v_pk_mul_f32 v[22:23], v[46:47], v[22:23]
	s_nop 0
	v_pk_fma_f32 v[28:29], v[28:29], v[24:25], v[22:23]
	global_load_dwordx4 v[22:25], v[38:39], off offset:16
	global_load_dwordx4 v[50:53], v[38:39], off
	s_waitcnt vmcnt(0)
	v_pk_fma_f32 v[34:35], v[50:51], v[26:27], v[28:29]
	global_load_dwordx4 v[26:29], v[42:43], off offset:16
	global_load_dwordx4 v[54:57], v[42:43], off
	s_waitcnt vmcnt(0)
	v_pk_add_f32 v[34:35], v[54:55], v[34:35]
	s_nop 0
	v_mul_f32_e32 v0, 0xbfb8aa3b, v34
	v_exp_f32_e32 v46, v0
	v_mul_f32_e32 v0, 0xbfb8aa3b, v35
	v_exp_f32_e32 v47, v0
	s_nop 0
	v_pk_add_f32 v[46:47], v[46:47], 1.0 op_sel_hi:[1,0]
	s_nop 0
	v_div_scale_f32 v0, s[2:3], v47, v47, v35
	v_rcp_f32_e32 v4, v0
	s_nop 0
	v_fma_f32 v10, -v0, v4, 1.0
	v_fmac_f32_e32 v4, v10, v4
	v_div_scale_f32 v10, vcc, v35, v47, v35
	v_mul_f32_e32 v33, v10, v4
	v_fma_f32 v37, -v0, v33, v10
	v_fmac_f32_e32 v33, v37, v4
	v_fma_f32 v0, -v0, v33, v10
	v_div_fmas_f32 v0, v0, v4, v33
	v_div_fixup_f32 v4, v0, v47, v35
	v_div_scale_f32 v0, s[2:3], v46, v46, v34
	v_rcp_f32_e32 v10, v0
	v_and_b32_e32 v47, 0xffff0000, v5
	v_fma_f32 v33, -v0, v10, 1.0
	v_fmac_f32_e32 v10, v33, v10
	v_div_scale_f32 v33, vcc, v34, v46, v34
	v_mul_f32_e32 v35, v33, v10
	v_fma_f32 v37, -v0, v35, v33
	v_fmac_f32_e32 v35, v37, v10
	v_fma_f32 v0, -v0, v35, v33
	v_div_fmas_f32 v0, v0, v10, v35
	v_div_fixup_f32 v10, v0, v46, v34
	v_lshlrev_b32_e32 v34, 16, v11
	v_and_b32_e32 v35, 0xffff0000, v11
	v_lshlrev_b32_e32 v46, 16, v5
	v_pk_mul_f32 v[34:35], v[48:49], v[34:35]
	v_lshlrev_b32_e32 v0, 16, v1
	v_and_b32_e32 v1, 0xffff0000, v1
	v_pk_fma_f32 v[30:31], v[30:31], v[46:47], v[34:35]
	v_mov_b32_e32 v37, v9
	v_pk_fma_f32 v[0:1], v[52:53], v[0:1], v[30:31]
	s_nop 0
	v_pk_add_f32 v[0:1], v[56:57], v[0:1]
	s_nop 0
	v_mul_f32_e32 v5, 0xbfb8aa3b, v0
	v_exp_f32_e32 v30, v5
	v_mul_f32_e32 v5, 0xbfb8aa3b, v1
	v_exp_f32_e32 v31, v5
	s_nop 0
	v_pk_add_f32 v[30:31], v[30:31], 1.0 op_sel_hi:[1,0]
	s_nop 0
	v_div_scale_f32 v5, s[2:3], v31, v31, v1
	v_rcp_f32_e32 v11, v5
	s_nop 0
	v_fma_f32 v33, -v5, v11, 1.0
	v_fmac_f32_e32 v11, v33, v11
	v_div_scale_f32 v33, vcc, v1, v31, v1
	v_mul_f32_e32 v34, v33, v11
	v_fma_f32 v35, -v5, v34, v33
	v_fmac_f32_e32 v34, v35, v11
	v_fma_f32 v5, -v5, v34, v33
	v_div_fmas_f32 v5, v5, v11, v34
	v_div_fixup_f32 v5, v5, v31, v1
	v_div_scale_f32 v1, s[2:3], v30, v30, v0
	v_rcp_f32_e32 v11, v1
	v_and_b32_e32 v35, 0xffff0000, v2
	v_fma_f32 v31, -v1, v11, 1.0
	v_fmac_f32_e32 v11, v31, v11
	v_div_scale_f32 v31, vcc, v0, v30, v0
	v_mul_f32_e32 v33, v31, v11
	v_fma_f32 v34, -v1, v33, v31
	v_fmac_f32_e32 v33, v34, v11
	v_fma_f32 v1, -v1, v33, v31
	v_div_fmas_f32 v1, v1, v11, v33
	v_div_fixup_f32 v11, v1, v30, v0
	v_lshlrev_b32_e32 v0, 16, v12
	v_and_b32_e32 v1, 0xffff0000, v12
	v_lshlrev_b32_e32 v30, 16, v6
	v_and_b32_e32 v31, 0xffff0000, v6
	v_pk_mul_f32 v[0:1], v[18:19], v[0:1]
	v_lshlrev_b32_e32 v34, 16, v2
	v_pk_fma_f32 v[0:1], v[14:15], v[30:31], v[0:1]
	s_nop 0
	v_pk_fma_f32 v[0:1], v[22:23], v[34:35], v[0:1]
	s_nop 0
	v_pk_add_f32 v[0:1], v[26:27], v[0:1]
	s_nop 0
	v_mul_f32_e32 v2, 0xbfb8aa3b, v0
	v_exp_f32_e32 v14, v2
	v_mul_f32_e32 v2, 0xbfb8aa3b, v1
	v_exp_f32_e32 v15, v2
	s_nop 0
	v_pk_add_f32 v[14:15], v[14:15], 1.0 op_sel_hi:[1,0]
	s_nop 0
	v_div_scale_f32 v2, s[2:3], v15, v15, v1
	v_rcp_f32_e32 v6, v2
	s_nop 0
	v_fma_f32 v12, -v2, v6, 1.0
	v_fmac_f32_e32 v6, v12, v6
	v_div_scale_f32 v12, vcc, v1, v15, v1
	v_mul_f32_e32 v18, v12, v6
	v_fma_f32 v19, -v2, v18, v12
	v_fmac_f32_e32 v18, v19, v6
	v_fma_f32 v2, -v2, v18, v12
	v_div_fmas_f32 v2, v2, v6, v18
	v_div_fixup_f32 v12, v2, v15, v1
	v_div_scale_f32 v1, s[2:3], v14, v14, v0
	v_rcp_f32_e32 v2, v1
	s_nop 0
	v_fma_f32 v6, -v1, v2, 1.0
	v_fmac_f32_e32 v2, v6, v2
	v_div_scale_f32 v6, vcc, v0, v14, v0
	v_mul_f32_e32 v15, v6, v2
	v_fma_f32 v18, -v1, v15, v6
	v_fmac_f32_e32 v15, v18, v2
	v_fma_f32 v1, -v1, v15, v6
	v_div_fmas_f32 v1, v1, v2, v15
	v_div_fixup_f32 v14, v1, v14, v0
	v_lshlrev_b32_e32 v0, 16, v13
	v_and_b32_e32 v1, 0xffff0000, v13
	v_lshlrev_b32_e32 v6, 16, v7
	v_and_b32_e32 v7, 0xffff0000, v7
	v_pk_mul_f32 v[0:1], v[20:21], v[0:1]
	v_lshlrev_b32_e32 v2, 16, v3
	v_and_b32_e32 v3, 0xffff0000, v3
	v_pk_fma_f32 v[0:1], v[16:17], v[6:7], v[0:1]
	s_nop 0
	v_pk_fma_f32 v[0:1], v[24:25], v[2:3], v[0:1]
	s_nop 0
	v_pk_add_f32 v[0:1], v[28:29], v[0:1]
	s_nop 0
	v_mul_f32_e32 v2, 0xbfb8aa3b, v0
	v_mul_f32_e32 v3, 0xbfb8aa3b, v1
	v_exp_f32_e32 v2, v2
	v_exp_f32_e32 v3, v3
	s_nop 0
	v_pk_add_f32 v[2:3], v[2:3], 1.0 op_sel_hi:[1,0]
	s_nop 0
	v_div_scale_f32 v6, s[2:3], v3, v3, v1
	v_rcp_f32_e32 v7, v6
	s_nop 0
	v_fma_f32 v13, -v6, v7, 1.0
	v_fmac_f32_e32 v7, v13, v7
	v_div_scale_f32 v13, vcc, v1, v3, v1
	v_mul_f32_e32 v15, v13, v7
	v_fma_f32 v16, -v6, v15, v13
	v_fmac_f32_e32 v15, v16, v7
	v_fma_f32 v6, -v6, v15, v13
	v_div_fmas_f32 v6, v6, v7, v15
	v_div_fixup_f32 v3, v6, v3, v1
	v_div_scale_f32 v1, s[2:3], v2, v2, v0
	v_rcp_f32_e32 v6, v1
	v_readlane_b32 s2, v251, 43
	v_readlane_b32 s3, v251, 44
	v_fma_f32 v7, -v1, v6, 1.0
	v_fmac_f32_e32 v6, v7, v6
	v_div_scale_f32 v7, vcc, v0, v2, v0
	v_mul_f32_e32 v13, v7, v6
	v_fma_f32 v15, -v1, v13, v7
	v_fmac_f32_e32 v13, v15, v6
	v_fma_f32 v1, -v1, v13, v7
	v_div_fmas_f32 v1, v1, v6, v13
	v_div_fixup_f32 v6, v1, v2, v0
	v_cvt_pk_bf16_f32 v0, v10, v4
	v_cvt_pk_bf16_f32 v1, v11, v5
	v_mov_b64_e32 v[4:5], s[2:3]
	s_movk_i32 s2, 0x600
	v_mad_i64_i32 v[4:5], s[2:3], v32, s2, v[4:5]
	s_mov_b32 s2, 0x110000
	v_cvt_pk_bf16_f32 v2, v14, v12
	v_cvt_pk_bf16_f32 v3, v6, v3
	v_lshl_add_u64 v[4:5], v[4:5], 0, v[36:37]
	v_cmp_gt_i32_e32 vcc, s2, v8
	global_store_dwordx4 v[4:5], v[0:3], off
	s_and_saveexec_b64 s[18:19], vcc
	s_cbranch_execz .LBB0_338
	v_ashrrev_i32_e32 v32, 5, v8
	s_mov_b32 s2, 0x8000
	v_cmp_gt_i32_e32 vcc, s2, v32
	v_mov_b64_e32 v[4:5], s[70:71]
	v_mad_i64_i32 v[4:5], s[2:3], v32, s77, v[4:5]
	v_cndmask_b32_e32 v1, v222, v223, vcc
	v_and_b32_e32 v2, v1, v32
	v_lshl_add_u64 v[4:5], v[4:5], 0, v[36:37]
	s_mov_b64 s[2:3], 0x1400
	v_mov_b32_e32 v0, 0
	v_cmp_ne_u32_e32 vcc, 0, v2
	v_lshl_add_u64 v[14:15], v[4:5], 0, s[2:3]
	v_mov_b32_e32 v4, 0
	v_mov_b32_e32 v5, 0
	v_mov_b32_e32 v6, 0
	v_mov_b32_e32 v7, 0
	s_and_saveexec_b64 s[24:25], vcc
	v_add_co_u32_e32 v4, vcc, 0xfffff000, v14
	s_nop 1
	v_addc_co_u32_e32 v5, vcc, -1, v15, vcc
	global_load_dwordx4 v[4:7], v[4:5], off offset:-3072

.LBB0_363:
	v_and_b32_e32 v5, 0x1c0, v77
	v_and_b32_e32 v79, 24, v76
	v_or_b32_e32 v0, v5, v79
	v_ashrrev_i32_e32 v80, 5, v78
	s_mov_b32 s0, 0x8000
	v_add_u32_e32 v4, 0x100, v0
	v_mov_b64_e32 v[0:1], s[70:71]
	v_cmp_gt_i32_e64 s[6:7], s0, v80
	v_mad_i64_i32 v[0:1], s[2:3], v80, s77, v[0:1]
	s_nop 0
	v_cndmask_b32_e64 v6, v222, v223, s[6:7]
	s_mov_b64 s[2:3], 0x1400
	v_and_b32_e32 v7, v6, v80
	v_lshl_add_u64 v[0:1], v[0:1], 0, s[2:3]
	v_lshlrev_b32_e32 v68, 1, v4
	v_mov_b32_e32 v69, v9
	v_mov_b32_e32 v14, 0
	v_cmp_ne_u32_e64 s[0:1], 0, v7
	v_lshl_add_u64 v[2:3], v[0:1], 0, v[68:69]
	v_add_u32_e32 v192, s34, v78
	v_cmp_gt_i32_e64 s[30:31], s32, v192
	s_nop 1
	v_cndmask_b32_e64 v190, 0, v205, s[30:31]
	v_cndmask_b32_e64 v192, 0, v204, s[30:31]
	v_lshl_add_u64 v[186:187], v[2:3], 0, v[190:191]
	v_lshl_add_u64 v[188:189], v[2:3], 0, v[192:193]
	v_mov_b32_e32 v18, 0
	v_mov_b32_e32 v19, 0
	v_mov_b32_e32 v20, 0
	v_mov_b32_e32 v21, 0
	s_and_saveexec_b64 s[4:5], s[0:1]
	v_add_co_u32_e32 v10, vcc, 0xfffff000, v2
	s_nop 1
	v_addc_co_u32_e32 v11, vcc, -1, v3, vcc
	global_load_dwordx4 v[18:21], v[10:11], off offset:-3072
.LBB0_365:
	s_or_b64 exec, exec, s[4:5]
	global_load_dwordx4 v[22:25], v[2:3], off
	v_cmp_ne_u32_e64 s[4:5], v7, v6
	v_mov_b32_e32 v15, 0
	v_mov_b32_e32 v16, 0
	v_mov_b32_e32 v17, 0
	s_and_saveexec_b64 s[18:19], s[4:5]
	v_add_co_u32_e32 v2, vcc, 0x1000, v2
	s_nop 1
	v_addc_co_u32_e32 v3, vcc, 0, v3, vcc
	global_load_dwordx4 v[14:17], v[2:3], off offset:3072
.LBB0_367:
	s_or_b64 exec, exec, s[18:19]
	v_add_u32_e32 v69, v5, v79
	v_readlane_b32 s18, v254, 50
	v_lshlrev_b32_e32 v8, 2, v69
	v_readlane_b32 s19, v254, 51
	s_mov_b64 s[2:3], 0x400
	v_mov_b32_e32 v75, v9
	v_lshl_add_u64 v[62:63], s[18:19], 0, v[8:9]
	v_lshl_add_u64 v[70:71], v[62:63], 0, s[2:3]
	s_mov_b64 s[2:3], 0x1c00
	v_lshl_add_u64 v[72:73], v[62:63], 0, s[2:3]
	v_add_co_u32_e32 v2, vcc, 0x1000, v62
	v_readlane_b32 s2, v254, 52
	s_nop 0
	v_addc_co_u32_e32 v3, vcc, 0, v63, vcc
	v_readlane_b32 s3, v254, 53
	v_mov_b64_e32 v[26:27], v[104:105]
	v_mov_b64_e32 v[28:29], v[106:107]
	v_mov_b64_e32 v[42:43], v[100:101]
	v_mov_b64_e32 v[44:45], v[102:103]
	v_mov_b64_e32 v[46:47], v[120:121]
	v_mov_b64_e32 v[48:49], v[122:123]
	v_mov_b64_e32 v[50:51], v[84:85]
	v_mov_b64_e32 v[52:53], v[86:87]
	v_mov_b64_e32 v[30:31], v[124:125]
	v_mov_b64_e32 v[32:33], v[126:127]
	v_mov_b64_e32 v[34:35], v[172:173]
	v_mov_b64_e32 v[36:37], v[174:175]
	v_mov_b64_e32 v[38:39], v[88:89]
	v_mov_b64_e32 v[40:41], v[90:91]
	v_mov_b64_e32 v[54:55], v[168:169]
	v_mov_b64_e32 v[56:57], v[170:171]
	v_or_b32_e32 v2, 32, v4
	v_lshlrev_b32_e32 v74, 1, v2
	v_lshl_add_u64 v[60:61], v[0:1], 0, v[74:75]
	v_mov_b32_e32 v4, 0
	v_mov_b32_e32 v0, 0
	v_mov_b32_e32 v1, 0
	v_mov_b32_e32 v2, 0
	v_mov_b32_e32 v3, 0
	s_and_saveexec_b64 s[18:19], s[0:1]
	v_add_co_u32_e32 v0, vcc, 0xfffff000, v60
	s_nop 1
	v_addc_co_u32_e32 v1, vcc, -1, v61, vcc
	global_load_dwordx4 v[0:3], v[0:1], off offset:-3072
.LBB0_369:
	s_or_b64 exec, exec, s[18:19]
	global_load_dwordx4 v[10:13], v[60:61], off
	v_mov_b32_e32 v5, 0
	v_mov_b32_e32 v6, 0
	v_mov_b32_e32 v7, 0
	s_and_saveexec_b64 s[0:1], s[4:5]
	v_add_co_u32_e32 v4, vcc, 0x1000, v60
	s_nop 1
	v_addc_co_u32_e32 v5, vcc, 0, v61, vcc
	global_load_dwordx4 v[4:7], v[4:5], off offset:3072

.LBB0_373:
	s_or_b64 exec, exec, s[0:1]
	v_readlane_b32 s0, v251, 43
	v_readlane_b32 s1, v251, 44
	v_lshlrev_b32_e32 v8, 1, v69
	v_cvt_pk_bf16_f32 v10, v46, v47
	v_mov_b64_e32 v[6:7], s[0:1]
	s_movk_i32 s0, 0x600
	v_mad_i64_i32 v[6:7], s[0:1], v80, s0, v[6:7]
	v_cvt_pk_bf16_f32 v11, v44, v45
	v_cvt_pk_bf16_f32 v12, v48, v49
	v_cvt_pk_bf16_f32 v13, v50, v51
	v_lshl_add_u64 v[6:7], v[6:7], 0, v[8:9]
	v_add_u32_e32 v80, s34, v78
	s_mov_b32 s0, 0x110000
	global_store_dwordx4 v[6:7], v[10:13], off offset:512
	v_cmp_gt_i32_e32 vcc, s0, v80
	s_mov_b64 s[0:1], -1
	v_cvt_pk_bf16_f32 v10, v32, v33
	v_cvt_pk_bf16_f32 v11, v0, v1
	v_cvt_pk_bf16_f32 v12, v4, v5
	v_cvt_pk_bf16_f32 v13, v2, v3
	global_store_dwordx4 v[6:7], v[10:13], off offset:576
	s_and_saveexec_b64 s[18:19], vcc
	s_cbranch_execz .LBB0_362
	v_ashrrev_i32_e32 v81, 5, v80
	s_mov_b32 s0, 0x8000
	v_mov_b64_e32 v[0:1], s[70:71]
	v_cmp_gt_i32_e64 s[6:7], s0, v81
	v_mad_i64_i32 v[0:1], s[2:3], v81, s77, v[0:1]
	s_nop 0
	v_cndmask_b32_e64 v4, v222, v223, s[6:7]
	s_mov_b64 s[2:3], 0x1400
	v_and_b32_e32 v5, v4, v81
	v_lshl_add_u64 v[0:1], v[0:1], 0, s[2:3]
	v_mov_b32_e32 v69, v9
	v_mov_b32_e32 v14, 0
	v_cmp_ne_u32_e64 s[0:1], 0, v5
	v_lshl_add_u64 v[2:3], v[0:1], 0, v[68:69]
	v_add_u32_e32 v192, s34, v80
	v_cmp_gt_i32_e64 s[30:31], s32, v192
	s_nop 1
	v_cndmask_b32_e64 v190, 0, v205, s[30:31]
	v_cndmask_b32_e64 v192, 0, v204, s[30:31]
	v_lshl_add_u64 v[186:187], v[2:3], 0, v[190:191]
	v_lshl_add_u64 v[188:189], v[2:3], 0, v[192:193]
	v_mov_b32_e32 v18, 0
	v_mov_b32_e32 v19, 0
	v_mov_b32_e32 v20, 0
	v_mov_b32_e32 v21, 0
	s_and_saveexec_b64 s[4:5], s[0:1]
	v_add_co_u32_e32 v6, vcc, 0xfffff000, v2
	s_nop 1
	v_addc_co_u32_e32 v7, vcc, -1, v3, vcc
	global_load_dwordx4 v[18:21], v[6:7], off offset:-3072
.LBB0_376:
	s_or_b64 exec, exec, s[4:5]
	global_load_dwordx4 v[22:25], v[2:3], off
	v_cmp_ne_u32_e64 s[4:5], v5, v4
	v_mov_b32_e32 v15, 0
	v_mov_b32_e32 v16, 0
	v_mov_b32_e32 v17, 0
	s_and_saveexec_b64 s[24:25], s[4:5]
	v_add_co_u32_e32 v2, vcc, 0x1000, v2
	s_nop 1
	v_addc_co_u32_e32 v3, vcc, 0, v3, vcc
	global_load_dwordx4 v[14:17], v[2:3], off offset:3072
.LBB0_378:
	s_or_b64 exec, exec, s[24:25]
	v_mov_b64_e32 v[26:27], v[88:89]
	v_mov_b64_e32 v[28:29], v[90:91]
	v_mov_b64_e32 v[42:43], v[84:85]
	v_mov_b64_e32 v[44:45], v[86:87]
	v_mov_b64_e32 v[30:31], v[104:105]
	v_mov_b64_e32 v[32:33], v[106:107]
	v_mov_b64_e32 v[54:55], v[100:101]
	v_mov_b64_e32 v[56:57], v[102:103]
	v_mov_b64_e32 v[34:35], v[124:125]
	v_mov_b64_e32 v[36:37], v[126:127]
	v_mov_b64_e32 v[46:47], v[120:121]
	v_mov_b64_e32 v[48:49], v[122:123]
	v_mov_b64_e32 v[38:39], v[172:173]
	v_mov_b64_e32 v[40:41], v[174:175]
	v_mov_b64_e32 v[50:51], v[168:169]
	v_mov_b64_e32 v[52:53], v[170:171]
	v_mov_b32_e32 v75, v9
	v_lshl_add_u64 v[68:69], v[0:1], 0, v[74:75]
	v_mov_b32_e32 v4, 0
	v_mov_b32_e32 v0, 0
	v_mov_b32_e32 v1, 0
	v_mov_b32_e32 v2, 0
	v_mov_b32_e32 v3, 0
	s_and_saveexec_b64 s[24:25], s[0:1]
	v_add_co_u32_e32 v0, vcc, 0xfffff000, v68
	s_nop 1
	v_addc_co_u32_e32 v1, vcc, -1, v69, vcc
	global_load_dwordx4 v[0:3], v[0:1], off offset:-3072
.LBB0_380:
	s_or_b64 exec, exec, s[24:25]
	global_load_dwordx4 v[10:13], v[68:69], off
	v_mov_b32_e32 v5, 0
	v_mov_b32_e32 v6, 0
	v_mov_b32_e32 v7, 0
	s_and_saveexec_b64 s[0:1], s[4:5]
	v_add_co_u32_e32 v4, vcc, 0x1000, v68
	s_nop 1
	v_addc_co_u32_e32 v5, vcc, 0, v69, vcc
	global_load_dwordx4 v[4:7], v[4:5], off offset:3072
